# baseline (speedup 1.0000x reference)
; __device__ __forceinline__ unsigned cvt_pk_bf16(float lo, float hi) { unsigned r; asm volatile("v_cvt_pk_bf16_f32 %0, %1, %2" : "=v"(r) : "v"(lo), "v"(hi)); return r; }
; __device__ __forceinline__ float dot4(f32x4 a, f32x4 b) { return (a.x * b.x + a.y * b.y) + (a.z * b.z + a.w * b.w); }
; __device__ __forceinline__ void group_norm_rows(const float* Y, const float* RW, const LayerP& L, bf16* dst, int gw, int NGW, int lane) {
;     ...
;             const float* yr = Y + (size_t)m * D + gi * GW;
;             f32x4 a = ((const f32x4*)yr)[lane], b = ((const f32x4*)yr)[64 + lane];
;             if (gi == 2) {
;                 const int ca = 4 * lane, cb = 256 + 4 * lane;
;                 const float ma = row16_sum((a.x + a.y) + (a.z + a.w)) * (1.f / 64.f), mb = row16_sum((b.x + b.y) + (b.z + b.w)) * (1.f / 64.f);
;                 const f32x4 da = a - ma, db = b - mb;
;                 const float ra = rsqrtf(row16_sum(dot4(da, da)) * (1.f / 64.f) + 64e-5f), rb = rsqrtf(row16_sum(dot4(db, db)) * (1.f / 64.f) + 64e-5f);
;                 const f32x4 ga = *(const f32x4*)(L.rw_lng + ca), gb = *(const f32x4*)(L.rw_lng + cb), ba = *(const f32x4*)(L.rw_lnb + ca), bb = *(const f32x4*)(L.rw_lnb + cb);
;                 const f32x4 bna = *(const f32x4*)(RW + 7 * RWSZ + (size_t)m * GW + ca), bnb = *(const f32x4*)(RW + 7 * RWSZ + (size_t)m * GW + cb);
;                 const f32x4 gga = *(const f32x4*)(RW + 6 * RWSZ + (size_t)m * GW + ca), ggb = *(const f32x4*)(RW + 6 * RWSZ + (size_t)m * GW + cb);
;                 a = (da * ra * ga + ba + bna) * gga; b = (db * rb * gb + bb + bnb) * ggb;
;             }
;             const float ss = wave_sum(dot4(a, a) + dot4(b, b));
;             const float rstd = rsqrtf(ss * (1.f / GW) + 1e-6f);
;             const f32x4 na = ((const f32x4*)(L.out_norm + gi * GW))[lane], nb = ((const f32x4*)(L.out_norm + gi * GW))[64 + lane];
;             const f32x4 oa = a * rstd * na, ob = b * rstd * nb;
;             u32x2 w; w.x = pg8::cvt_pk_bf16(oa.x, oa.y); w.y = pg8::cvt_pk_bf16(oa.z, oa.w); ((u32x2*)(dst + (size_t)m * D + gi * GW))[lane] = w;
;             w.x = pg8::cvt_pk_bf16(ob.x, ob.y); w.y = pg8::cvt_pk_bf16(ob.z, ob.w); ((u32x2*)(dst + (size_t)m * D + gi * GW))[64 + lane] = w;
.Lgn2_row:
	s_mov_b32 s31, s30
	s_lshl_b32 s0, s31, 13
	s_add_u32 s20, s18, s0
	s_addc_u32 s21, s19, 0
	s_add_u32 s20, s20, 0x1e200000
	s_addc_u32 s21, s21, 0
	s_lshl_b32 s0, s31, 11
	s_add_u32 s22, s18, s0
	s_addc_u32 s23, s19, 0
	s_add_u32 s24, s22, 0x1d200000
	s_addc_u32 s25, s23, 0
	s_add_u32 s22, s22, 0x1c200000
	s_addc_u32 s23, s23, 0
	global_load_dwordx4 v[128:131], v1, s[20:21]
	global_load_dwordx4 v[132:135], v1, s[20:21] offset:1024
	global_load_dwordx4 v[136:139], v0, s[24:25]
	global_load_dwordx4 v[140:143], v0, s[24:25] offset:1024
	global_load_dwordx4 v[152:155], v0, s[22:23]
	global_load_dwordx4 v[156:159], v0, s[22:23] offset:1024
	s_waitcnt vmcnt(0)
.Lgn2_loop:
	v_mov_b64_e32 v[32:33], v[128:129]
	v_mov_b64_e32 v[34:35], v[130:131]
	v_mov_b64_e32 v[36:37], v[132:133]
	v_mov_b64_e32 v[38:39], v[134:135]
	v_mov_b64_e32 v[48:49], v[136:137]
	v_mov_b64_e32 v[50:51], v[138:139]
	v_mov_b64_e32 v[52:53], v[140:141]
	v_mov_b64_e32 v[54:55], v[142:143]
	v_mov_b64_e32 v[56:57], v[152:153]
	v_mov_b64_e32 v[58:59], v[154:155]
	v_mov_b64_e32 v[60:61], v[156:157]
	v_mov_b64_e32 v[62:63], v[158:159]
	s_lshl_b32 s0, s30, 12
	s_add_u32 s26, s18, s0
	s_addc_u32 s27, s19, 0
	s_add_u32 s26, s26, 0x22200000
	s_addc_u32 s27, s27, 0
	s_add_i32 s31, s30, s14
	s_cmpk_gt_i32 s31, 0x1fff
	s_cbranch_scc1 .Lgn2_nopref
	s_lshl_b32 s0, s31, 13
	s_add_u32 s20, s18, s0
	s_addc_u32 s21, s19, 0
	s_add_u32 s20, s20, 0x1e200000
	s_addc_u32 s21, s21, 0
	s_lshl_b32 s0, s31, 11
	s_add_u32 s22, s18, s0
	s_addc_u32 s23, s19, 0
	s_add_u32 s24, s22, 0x1d200000
	s_addc_u32 s25, s23, 0
	s_add_u32 s22, s22, 0x1c200000
	s_addc_u32 s23, s23, 0
	global_load_dwordx4 v[128:131], v1, s[20:21]
	global_load_dwordx4 v[132:135], v1, s[20:21] offset:1024
	global_load_dwordx4 v[136:139], v0, s[24:25]
	global_load_dwordx4 v[140:143], v0, s[24:25] offset:1024
	global_load_dwordx4 v[152:155], v0, s[22:23]
	global_load_dwordx4 v[156:159], v0, s[22:23] offset:1024
; __device__ __forceinline__ unsigned cvt_pk_bf16(float lo, float hi) { unsigned r; asm volatile("v_cvt_pk_bf16_f32 %0, %1, %2" : "=v"(r) : "v"(lo), "v"(hi)); return r; }
; __device__ __forceinline__ float dot4(f32x4 a, f32x4 b) { return (a.x * b.x + a.y * b.y) + (a.z * b.z + a.w * b.w); }
; __device__ __forceinline__ void group_norm_rows(const float* Y, const float* RW, const LayerP& L, bf16* dst, int gw, int NGW, int lane) {
;     ...
;             if (gi == 2) {
;                 const int ca = 4 * lane, cb = 256 + 4 * lane;
;                 const float ma = row16_sum((a.x + a.y) + (a.z + a.w)) * (1.f / 64.f), mb = row16_sum((b.x + b.y) + (b.z + b.w)) * (1.f / 64.f);
;                 const f32x4 da = a - ma, db = b - mb;
;                 const float ra = rsqrtf(row16_sum(dot4(da, da)) * (1.f / 64.f) + 64e-5f), rb = rsqrtf(row16_sum(dot4(db, db)) * (1.f / 64.f) + 64e-5f);
;                 const f32x4 ga = *(const f32x4*)(L.rw_lng + ca), gb = *(const f32x4*)(L.rw_lng + cb), ba = *(const f32x4*)(L.rw_lnb + ca), bb = *(const f32x4*)(L.rw_lnb + cb);
;                 const f32x4 bna = *(const f32x4*)(RW + 7 * RWSZ + (size_t)m * GW + ca), bnb = *(const f32x4*)(RW + 7 * RWSZ + (size_t)m * GW + cb);
;                 const f32x4 gga = *(const f32x4*)(RW + 6 * RWSZ + (size_t)m * GW + ca), ggb = *(const f32x4*)(RW + 6 * RWSZ + (size_t)m * GW + cb);
;                 a = (da * ra * ga + ba + bna) * gga; b = (db * rb * gb + bb + bnb) * ggb;
;             }
;             const float ss = wave_sum(dot4(a, a) + dot4(b, b));
;             const float rstd = rsqrtf(ss * (1.f / GW) + 1e-6f);
;             const f32x4 na = ((const f32x4*)(L.out_norm + gi * GW))[lane], nb = ((const f32x4*)(L.out_norm + gi * GW))[64 + lane];
;             const f32x4 oa = a * rstd * na, ob = b * rstd * nb;
;             u32x2 w; w.x = pg8::cvt_pk_bf16(oa.x, oa.y); w.y = pg8::cvt_pk_bf16(oa.z, oa.w); ((u32x2*)(dst + (size_t)m * D + gi * GW))[lane] = w;
;             w.x = pg8::cvt_pk_bf16(ob.x, ob.y); w.y = pg8::cvt_pk_bf16(ob.z, ob.w); ((u32x2*)(dst + (size_t)m * D + gi * GW))[64 + lane] = w;
.Lgn2_nopref:
	v_add_f32_e32 v64, v32, v33
	v_add_f32_e32 v3, v34, v35
	v_add_f32_e32 v64, v64, v3
	v_add_f32_e32 v65, v36, v37
	v_add_f32_e32 v3, v38, v39
	v_add_f32_e32 v65, v65, v3
	s_nop 1
	v_add_f32_dpp v64, v64, v64 quad_perm:[1,0,3,2] row_mask:0xf bank_mask:0xf bound_ctrl:1
	v_add_f32_dpp v65, v65, v65 quad_perm:[1,0,3,2] row_mask:0xf bank_mask:0xf bound_ctrl:1
	s_nop 1
	v_add_f32_dpp v64, v64, v64 quad_perm:[2,3,0,1] row_mask:0xf bank_mask:0xf bound_ctrl:1
	v_add_f32_dpp v65, v65, v65 quad_perm:[2,3,0,1] row_mask:0xf bank_mask:0xf bound_ctrl:1
	s_nop 1
	v_add_f32_dpp v64, v64, v64 row_half_mirror row_mask:0xf bank_mask:0xf bound_ctrl:1
	v_add_f32_dpp v65, v65, v65 row_half_mirror row_mask:0xf bank_mask:0xf bound_ctrl:1
	s_nop 1
	v_add_f32_dpp v64, v64, v64 row_mirror row_mask:0xf bank_mask:0xf bound_ctrl:1
	v_add_f32_dpp v65, v65, v65 row_mirror row_mask:0xf bank_mask:0xf bound_ctrl:1
	v_mul_f32_e32 v64, 0x3c800000, v64
	v_mul_f32_e32 v65, 0x3c800000, v65
	v_sub_f32_e32 v32, v32, v64
	v_sub_f32_e32 v36, v36, v65
	v_sub_f32_e32 v33, v33, v64
	v_sub_f32_e32 v37, v37, v65
	v_sub_f32_e32 v34, v34, v64
	v_sub_f32_e32 v38, v38, v65
	v_sub_f32_e32 v35, v35, v64
	v_sub_f32_e32 v39, v39, v65
	v_mul_f32_e32 v66, v32, v32
	v_fmac_f32_e32 v66, v33, v33
	v_mul_f32_e32 v3, v34, v34
	v_fmac_f32_e32 v3, v35, v35
	v_add_f32_e32 v66, v66, v3
	v_mul_f32_e32 v67, v36, v36
	v_fmac_f32_e32 v67, v37, v37
	v_mul_f32_e32 v3, v38, v38
	v_fmac_f32_e32 v3, v39, v39
	v_add_f32_e32 v67, v67, v3
	s_nop 1
	v_add_f32_dpp v66, v66, v66 quad_perm:[1,0,3,2] row_mask:0xf bank_mask:0xf bound_ctrl:1
	v_add_f32_dpp v67, v67, v67 quad_perm:[1,0,3,2] row_mask:0xf bank_mask:0xf bound_ctrl:1
	s_nop 1
	v_add_f32_dpp v66, v66, v66 quad_perm:[2,3,0,1] row_mask:0xf bank_mask:0xf bound_ctrl:1
	v_add_f32_dpp v67, v67, v67 quad_perm:[2,3,0,1] row_mask:0xf bank_mask:0xf bound_ctrl:1
	s_nop 1
	v_add_f32_dpp v66, v66, v66 row_half_mirror row_mask:0xf bank_mask:0xf bound_ctrl:1
	v_add_f32_dpp v67, v67, v67 row_half_mirror row_mask:0xf bank_mask:0xf bound_ctrl:1
	s_nop 1
	v_add_f32_dpp v66, v66, v66 row_mirror row_mask:0xf bank_mask:0xf bound_ctrl:1
	v_add_f32_dpp v67, v67, v67 row_mirror row_mask:0xf bank_mask:0xf bound_ctrl:1
	v_mov_b32_e32 v3, 0x3c800000
	v_mov_b32_e32 v5, 0x3a27c5ac
	v_fma_f32 v66, v66, v3, v5
	v_fma_f32 v67, v67, v3, v5
	v_rsq_f32_e32 v66, v66
	v_rsq_f32_e32 v67, v67
	s_nop 0
	v_mul_f32_e32 v32, v32, v66
	v_fma_f32 v32, v32, v112, v120
	v_add_f32_e32 v32, v32, v48
	v_mul_f32_e32 v32, v32, v56
	v_mul_f32_e32 v36, v36, v67
	v_fma_f32 v36, v36, v116, v124
	v_add_f32_e32 v36, v36, v52
	v_mul_f32_e32 v36, v36, v60
	v_mul_f32_e32 v33, v33, v66
	v_fma_f32 v33, v33, v113, v121
	v_add_f32_e32 v33, v33, v49
	v_mul_f32_e32 v33, v33, v57
	v_mul_f32_e32 v37, v37, v67
	v_fma_f32 v37, v37, v117, v125
	v_add_f32_e32 v37, v37, v53
	v_mul_f32_e32 v37, v37, v61
	v_mul_f32_e32 v34, v34, v66
	v_fma_f32 v34, v34, v114, v122
	v_add_f32_e32 v34, v34, v50
	v_mul_f32_e32 v34, v34, v58
	v_mul_f32_e32 v38, v38, v67
	v_fma_f32 v38, v38, v118, v126
	v_add_f32_e32 v38, v38, v54
	v_mul_f32_e32 v38, v38, v62
	v_mul_f32_e32 v35, v35, v66
	v_fma_f32 v35, v35, v115, v123
	v_add_f32_e32 v35, v35, v51
	v_mul_f32_e32 v35, v35, v59
	v_mul_f32_e32 v39, v39, v67
	v_fma_f32 v39, v39, v119, v127
	v_add_f32_e32 v39, v39, v55
	v_mul_f32_e32 v39, v39, v63
	v_mul_f32_e32 v3, v32, v32
	v_fmac_f32_e32 v3, v33, v33
	v_mul_f32_e32 v4, v34, v34
	v_fmac_f32_e32 v4, v35, v35
	v_add_f32_e32 v3, v3, v4
	v_mul_f32_e32 v5, v36, v36
	v_fmac_f32_e32 v5, v37, v37
	v_mul_f32_e32 v6, v38, v38
	v_fmac_f32_e32 v6, v39, v39
	v_add_f32_e32 v5, v5, v6
	v_add_f32_e32 v3, v3, v5
	s_nop 1
	v_add_f32_dpp v3, v3, v3 quad_perm:[1,0,3,2] row_mask:0xf bank_mask:0xf bound_ctrl:1
	s_nop 1
	v_add_f32_dpp v3, v3, v3 quad_perm:[2,3,0,1] row_mask:0xf bank_mask:0xf bound_ctrl:1
	s_nop 1
	v_add_f32_dpp v3, v3, v3 row_half_mirror row_mask:0xf bank_mask:0xf bound_ctrl:1
	s_nop 1
	v_add_f32_dpp v3, v3, v3 row_mirror row_mask:0xf bank_mask:0xf bound_ctrl:1
	s_nop 1
	v_readlane_b32 s0, v3, 0
	v_readlane_b32 s1, v3, 16
	v_readlane_b32 s8, v3, 32
	v_readlane_b32 s9, v3, 48
	s_nop 1
	v_mov_b32_e32 v4, s0
	v_add_f32_e32 v4, s1, v4
	v_add_f32_e32 v4, s8, v4
	v_add_f32_e32 v4, s9, v4
	v_mov_b32_e32 v5, 0x3b000000
	v_fma_f32 v4, v4, v5, v173
	v_rsq_f32_e32 v4, v4
	s_nop 0
	v_mul_f32_e32 v8, v32, v4
	v_mul_f32_e32 v8, v8, v96
	v_mul_f32_e32 v9, v33, v4
	v_mul_f32_e32 v9, v9, v97
	v_mul_f32_e32 v10, v34, v4
	v_mul_f32_e32 v10, v10, v98
	v_mul_f32_e32 v11, v35, v4
	v_mul_f32_e32 v11, v11, v99
	v_cvt_pk_bf16_f32 v12, v8, v9
	v_cvt_pk_bf16_f32 v13, v10, v11
	global_store_dwordx2 v2, v[12:13], s[26:27] offset:2048
	v_mul_f32_e32 v8, v36, v4
	v_mul_f32_e32 v8, v8, v100
	v_mul_f32_e32 v9, v37, v4
	v_mul_f32_e32 v9, v9, v101
	v_mul_f32_e32 v10, v38, v4
	v_mul_f32_e32 v10, v10, v102
	v_mul_f32_e32 v11, v39, v4
	v_mul_f32_e32 v11, v11, v103
	v_cvt_pk_bf16_f32 v12, v8, v9
	v_cvt_pk_bf16_f32 v13, v10, v11
	global_store_dwordx2 v2, v[12:13], s[26:27] offset:2560
	s_mov_b32 s30, s31
	s_cmpk_gt_i32 s30, 0x1fff
	s_cbranch_scc1 .LBB0_65
	s_waitcnt vmcnt(2)
	s_branch .Lgn2_loop
